# combo21 + p6a_prep unit order head-fastest (full 2 KB rows touched by 8 workgroups at the same time)
# baseline (speedup 1.0000x reference)
.LBB0_552:
	s_bfe_u32 s50, s48, 0x30000
	s_lshl_b32 s51, s50, 7
	v_readlane_b32 s76, v247, 26
	v_or_b32_e32 v0, s51, v20
	v_readlane_b32 s82, v247, 32
	v_readlane_b32 s83, v247, 33
	v_lshlrev_b32_e32 v22, 2, v0
	s_mov_b64 s[54:55], s[82:83]
	v_lshl_add_u64 v[0:1], s[54:55], 0, v[22:23]
	s_ashr_i32 s42, s48, 10
	v_add_co_u32_e32 v0, vcc, 0x1000, v0
	s_bfe_u32 s49, s48, 0x70003
	s_nop 0
	v_addc_co_u32_e32 v1, vcc, 0, v1, vcc
	s_ashr_i32 s43, s42, 31
	global_load_dwordx2 v[0:1], v[0:1], off
	s_nop 0
	global_load_dwordx2 v[2:3], v22, s[82:83]
	s_lshl_b64 s[44:45], s[42:43], 23
	v_lshl_add_u32 v22, s49, 16, v94
	v_lshl_add_u64 v[4:5], s[44:45], 0, v[22:23]
	v_or_b32_e32 v4, s51, v4
	v_or_b32_e32 v4, v4, v20
	v_lshlrev_b64 v[26:27], 1, v[4:5]
	v_lshl_add_u64 v[34:35], s[34:35], 0, v[26:27]
	v_add_co_u32_e32 v4, vcc, s33, v34
	v_lshl_add_u64 v[32:33], s[36:37], 0, v[26:27]
	s_nop 0
	v_addc_co_u32_e32 v5, vcc, 0, v35, vcc
	v_add_co_u32_e32 v6, vcc, s33, v32
	v_lshl_add_u64 v[30:31], s[38:39], 0, v[26:27]
	s_nop 0
	v_addc_co_u32_e32 v7, vcc, 0, v33, vcc
	global_load_dword v16, v[32:33], off
	global_load_dword v46, v[30:31], off offset:2048
	global_load_dword v99, v[4:5], off offset:2048
	global_load_dword v17, v[6:7], off offset:2048
	global_load_dword v18, v[32:33], off offset:2048
	v_add_co_u32_e32 v4, vcc, s46, v32
	v_readlane_b32 s77, v247, 27
	s_nop 0
	v_addc_co_u32_e32 v5, vcc, 0, v33, vcc
	v_add_co_u32_e32 v6, vcc, s46, v34
	global_load_dword v19, v[4:5], off offset:-4096
	global_load_dword v28, v[4:5], off
	v_addc_co_u32_e32 v7, vcc, 0, v35, vcc
	v_add_co_u32_e32 v8, vcc, s33, v30
	v_readlane_b32 s78, v247, 28
	s_nop 0
	v_addc_co_u32_e32 v9, vcc, 0, v31, vcc
	v_add_co_u32_e32 v10, vcc, s46, v30
	v_readlane_b32 s79, v247, 29
	s_nop 0
	v_addc_co_u32_e32 v11, vcc, 0, v31, vcc
	global_load_dword v47, v[10:11], off
	global_load_dword v52, v[10:11], off offset:2048
	global_load_dword v29, v[4:5], off offset:2048
	v_add_co_u32_e32 v4, vcc, s47, v34
	v_readlane_b32 s80, v247, 30
	s_nop 0
	v_addc_co_u32_e32 v5, vcc, 0, v35, vcc
	v_add_co_u32_e32 v12, vcc, s47, v32
	v_readlane_b32 s81, v247, 31
	s_nop 0
	v_addc_co_u32_e32 v13, vcc, 0, v33, vcc
	global_load_dword v36, v[12:13], off
	v_add_co_u32_e32 v14, vcc, s47, v30
	v_readlane_b32 s84, v247, 34
	s_nop 0
	v_addc_co_u32_e32 v15, vcc, 0, v31, vcc
	global_load_dword v53, v[30:31], off
	global_load_dword v112, v[34:35], off
	global_load_dword v113, v[34:35], off offset:2048
	global_load_dword v37, v[14:15], off offset:2048
	global_load_dword v38, v[12:13], off offset:2048
	global_load_dword v54, v[10:11], off offset:-4096
	global_load_dword v100, v[6:7], off
	global_load_dword v98, v[6:7], off offset:2048
	global_load_dword v55, v[14:15], off
	global_load_dword v101, v[6:7], off offset:-4096
	global_load_dword v60, v[8:9], off offset:2048
	global_load_dword v97, v[4:5], off
	global_load_dword v22, v[4:5], off offset:2048
	v_readlane_b32 s85, v247, 35
	v_readlane_b32 s86, v247, 36
	v_readlane_b32 s87, v247, 37
	v_readlane_b32 s88, v247, 38
	v_readlane_b32 s89, v247, 39
	v_readlane_b32 s90, v247, 40
	v_readlane_b32 s91, v247, 41
	s_waitcnt vmcnt(24)
	v_sub_f32_e32 v0, v0, v2
	v_sub_f32_e32 v1, v1, v3
	v_mul_f32_e32 v0, 0x3fb8aa3b, v0
	v_mul_f32_e32 v1, 0x3fb8aa3b, v1
	v_exp_f32_e32 v0, v0
	v_exp_f32_e32 v1, v1
	s_waitcnt vmcnt(23)
	v_lshlrev_b32_e32 v2, 16, v16
	v_pk_add_f32 v[0:1], v[0:1], 1.0 op_sel_hi:[1,0]
	s_waitcnt vmcnt(19)
	v_lshlrev_b32_e32 v4, 16, v18
	v_and_b32_e32 v5, 0xffff0000, v18
	v_div_scale_f32 v18, s[44:45], v1, v1, 1.0
	v_and_b32_e32 v3, 0xffff0000, v16
	v_mul_f32_e32 v2, 0xbfb8aa3b, v2
	v_mul_f32_e32 v3, 0xbfb8aa3b, v3
	s_waitcnt vmcnt(18)
	v_lshlrev_b32_e32 v6, 16, v19
	v_and_b32_e32 v7, 0xffff0000, v19
	v_rcp_f32_e32 v19, v18
	s_waitcnt vmcnt(17)
	v_lshlrev_b32_e32 v10, 16, v28
	v_and_b32_e32 v11, 0xffff0000, v28
	v_mul_f32_e32 v4, 0xbfb8aa3b, v4
	v_fma_f32 v28, -v18, v19, 1.0
	v_fmac_f32_e32 v19, v28, v19
	v_div_scale_f32 v28, vcc, 1.0, v1, 1.0
	v_mul_f32_e32 v5, 0xbfb8aa3b, v5
	v_exp_f32_e32 v2, v2
	v_exp_f32_e32 v3, v3
	v_exp_f32_e32 v4, v4
	s_waitcnt vmcnt(14)
	v_lshlrev_b32_e32 v12, 16, v29
	v_and_b32_e32 v13, 0xffff0000, v29
	v_mul_f32_e32 v29, v28, v19
	v_exp_f32_e32 v5, v5
	v_mul_f32_e32 v6, 0xbfb8aa3b, v6
	v_mul_f32_e32 v7, 0xbfb8aa3b, v7
	v_lshlrev_b32_e32 v8, 16, v17
	v_and_b32_e32 v9, 0xffff0000, v17
	v_exp_f32_e32 v6, v6
	v_exp_f32_e32 v7, v7
	v_mul_f32_e32 v8, 0xbfb8aa3b, v8
	s_waitcnt vmcnt(13)
	v_lshlrev_b32_e32 v14, 16, v36
	v_and_b32_e32 v15, 0xffff0000, v36
	v_fma_f32 v36, -v18, v29, v28
	v_fmac_f32_e32 v29, v36, v19
	v_fma_f32 v18, -v18, v29, v28
	v_div_scale_f32 v28, s[44:45], v0, v0, 1.0
	v_rcp_f32_e32 v36, v28
	v_div_fmas_f32 v18, v18, v19, v29
	v_div_fixup_f32 v1, v18, v1, 1.0
	v_mul_f32_e32 v9, 0xbfb8aa3b, v9
	v_fma_f32 v18, -v28, v36, 1.0
	v_fmac_f32_e32 v36, v18, v36
	v_div_scale_f32 v18, vcc, 1.0, v0, 1.0
	v_exp_f32_e32 v8, v8
	v_exp_f32_e32 v9, v9
	v_mul_f32_e32 v10, 0xbfb8aa3b, v10
	v_mul_f32_e32 v11, 0xbfb8aa3b, v11
	v_mul_f32_e32 v19, v18, v36
	v_exp_f32_e32 v10, v10
	v_exp_f32_e32 v11, v11
	v_mul_f32_e32 v12, 0xbfb8aa3b, v12
	v_mul_f32_e32 v13, 0xbfb8aa3b, v13
	v_fma_f32 v29, -v28, v19, v18
	v_add_f32_e32 v2, 1.0, v2
	v_add_f32_e32 v3, 1.0, v3
	v_add_f32_e32 v4, 1.0, v4
	v_add_f32_e32 v5, 1.0, v5
	v_exp_f32_e32 v12, v12
	v_exp_f32_e32 v13, v13
	v_mul_f32_e32 v14, 0xbfb8aa3b, v14
	v_mul_f32_e32 v15, 0xbfb8aa3b, v15
	s_waitcnt vmcnt(8)
	v_lshlrev_b32_e32 v16, 16, v38
	v_and_b32_e32 v17, 0xffff0000, v38
	v_fmac_f32_e32 v19, v29, v36
	v_rcp_f32_e32 v2, v2
	v_rcp_f32_e32 v3, v3
	v_rcp_f32_e32 v4, v4
	v_rcp_f32_e32 v5, v5
	v_add_f32_e32 v6, 1.0, v6
	v_add_f32_e32 v7, 1.0, v7
	v_exp_f32_e32 v14, v14
	v_exp_f32_e32 v15, v15
	v_mul_f32_e32 v16, 0xbfb8aa3b, v16
	v_mul_f32_e32 v17, 0xbfb8aa3b, v17
	v_fma_f32 v18, -v28, v19, v18
	v_rcp_f32_e32 v6, v6
	v_rcp_f32_e32 v7, v7
	v_add_f32_e32 v8, 1.0, v8
	v_add_f32_e32 v9, 1.0, v9
	v_exp_f32_e32 v16, v16
	v_exp_f32_e32 v17, v17
	v_div_fmas_f32 v18, v18, v36, v19
	v_rcp_f32_e32 v8, v8
	v_rcp_f32_e32 v9, v9
	v_add_f32_e32 v10, 1.0, v10
	v_add_f32_e32 v11, 1.0, v11
	v_div_fixup_f32 v0, v18, v0, 1.0
	v_rcp_f32_e32 v10, v10
	v_rcp_f32_e32 v11, v11
	v_add_f32_e32 v12, 1.0, v12
	v_add_f32_e32 v13, 1.0, v13
	v_pk_add_f32 v[18:19], v[0:1], 1.0 op_sel_hi:[1,0] neg_lo:[1,0] neg_hi:[1,0]
	v_rcp_f32_e32 v12, v12
	v_rcp_f32_e32 v13, v13
	v_add_f32_e32 v14, 1.0, v14
	v_add_f32_e32 v15, 1.0, v15
	v_pk_fma_f32 v[86:87], v[18:19], v[2:3], v[0:1]
	v_pk_fma_f32 v[78:79], v[18:19], v[4:5], v[0:1]
	v_lshlrev_b32_e32 v2, 16, v37
	v_and_b32_e32 v3, 0xffff0000, v37
	s_waitcnt vmcnt(4)
	v_lshlrev_b32_e32 v4, 16, v55
	v_and_b32_e32 v5, 0xffff0000, v55
	v_rcp_f32_e32 v14, v14
	v_rcp_f32_e32 v15, v15
	v_add_f32_e32 v16, 1.0, v16
	v_add_f32_e32 v17, 1.0, v17
	v_pk_fma_f32 v[64:65], v[18:19], v[6:7], v[0:1]
	v_mul_f32_e32 v2, 0xbfb8aa3b, v2
	v_mul_f32_e32 v3, 0xbfb8aa3b, v3
	v_mul_f32_e32 v4, 0xbfb8aa3b, v4
	v_mul_f32_e32 v5, 0xbfb8aa3b, v5
	v_lshlrev_b32_e32 v6, 16, v52
	v_and_b32_e32 v7, 0xffff0000, v52
	v_rcp_f32_e32 v16, v16
	v_rcp_f32_e32 v17, v17
	v_pk_fma_f32 v[56:57], v[18:19], v[8:9], v[0:1]
	v_exp_f32_e32 v2, v2
	v_exp_f32_e32 v3, v3
	v_exp_f32_e32 v4, v4
	v_exp_f32_e32 v5, v5
	v_mul_f32_e32 v6, 0xbfb8aa3b, v6
	v_mul_f32_e32 v7, 0xbfb8aa3b, v7
	v_lshlrev_b32_e32 v8, 16, v47
	v_and_b32_e32 v9, 0xffff0000, v47
	v_pk_fma_f32 v[48:49], v[18:19], v[10:11], v[0:1]
	v_exp_f32_e32 v6, v6
	v_exp_f32_e32 v7, v7
	v_mul_f32_e32 v8, 0xbfb8aa3b, v8
	v_mul_f32_e32 v9, 0xbfb8aa3b, v9
	s_waitcnt vmcnt(2)
	v_lshlrev_b32_e32 v10, 16, v60
	v_and_b32_e32 v11, 0xffff0000, v60
	v_pk_fma_f32 v[42:43], v[18:19], v[12:13], v[0:1]
	v_exp_f32_e32 v8, v8
	v_exp_f32_e32 v9, v9
	v_mul_f32_e32 v10, 0xbfb8aa3b, v10
	v_mul_f32_e32 v11, 0xbfb8aa3b, v11
	v_lshlrev_b32_e32 v12, 16, v54
	v_and_b32_e32 v13, 0xffff0000, v54
	v_pk_fma_f32 v[38:39], v[18:19], v[14:15], v[0:1]
	v_exp_f32_e32 v10, v10
	v_exp_f32_e32 v11, v11
	v_mul_f32_e32 v12, 0xbfb8aa3b, v12
	v_mul_f32_e32 v13, 0xbfb8aa3b, v13
	v_lshlrev_b32_e32 v14, 16, v46
	v_and_b32_e32 v15, 0xffff0000, v46
	v_pk_fma_f32 v[28:29], v[18:19], v[16:17], v[0:1]
	v_add_f32_e32 v2, 1.0, v2
	v_add_f32_e32 v3, 1.0, v3
	v_add_f32_e32 v4, 1.0, v4
	v_add_f32_e32 v5, 1.0, v5
	v_exp_f32_e32 v12, v12
	v_exp_f32_e32 v13, v13
	v_mul_f32_e32 v14, 0xbfb8aa3b, v14
	v_mul_f32_e32 v15, 0xbfb8aa3b, v15
	v_lshlrev_b32_e32 v16, 16, v53
	v_and_b32_e32 v17, 0xffff0000, v53
	v_rcp_f32_e32 v2, v2
	v_rcp_f32_e32 v3, v3
	v_rcp_f32_e32 v4, v4
	v_rcp_f32_e32 v5, v5
	v_add_f32_e32 v6, 1.0, v6
	v_add_f32_e32 v7, 1.0, v7
	v_exp_f32_e32 v14, v14
	v_exp_f32_e32 v15, v15
	v_mul_f32_e32 v16, 0xbfb8aa3b, v16
	v_mul_f32_e32 v17, 0xbfb8aa3b, v17
	v_rcp_f32_e32 v6, v6
	v_rcp_f32_e32 v7, v7
	v_add_f32_e32 v8, 1.0, v8
	v_add_f32_e32 v9, 1.0, v9
	v_exp_f32_e32 v16, v16
	v_exp_f32_e32 v17, v17
	v_rcp_f32_e32 v8, v8
	v_rcp_f32_e32 v9, v9
	v_add_f32_e32 v10, 1.0, v10
	v_add_f32_e32 v11, 1.0, v11
	v_rcp_f32_e32 v10, v10
	v_rcp_f32_e32 v11, v11
	v_add_f32_e32 v12, 1.0, v12
	v_add_f32_e32 v13, 1.0, v13
	v_rcp_f32_e32 v12, v12
	v_rcp_f32_e32 v13, v13
	v_add_f32_e32 v14, 1.0, v14
	v_add_f32_e32 v15, 1.0, v15
	v_pk_fma_f32 v[46:47], v[18:19], v[2:3], v[0:1]
	v_pk_fma_f32 v[54:55], v[18:19], v[4:5], v[0:1]
	v_pk_mul_f32 v[82:83], v[86:87], v[78:79]
	v_rcp_f32_e32 v14, v14
	v_rcp_f32_e32 v15, v15
	v_add_f32_e32 v16, 1.0, v16
	v_add_f32_e32 v17, 1.0, v17
	v_pk_mul_f32 v[60:61], v[54:55], v[46:47]
	v_pk_fma_f32 v[62:63], v[18:19], v[6:7], v[0:1]
	v_pk_mul_f32 v[72:73], v[82:83], v[64:65]
	v_rcp_f32_e32 v16, v16
	v_rcp_f32_e32 v17, v17
	v_pk_mul_f32 v[76:77], v[62:63], v[60:61]
	v_pk_fma_f32 v[80:81], v[18:19], v[8:9], v[0:1]
	v_pk_mul_f32 v[58:59], v[72:73], v[56:57]
	v_pk_mul_f32 v[84:85], v[80:81], v[76:77]
	v_pk_fma_f32 v[88:89], v[18:19], v[10:11], v[0:1]
	v_pk_mul_f32 v[50:51], v[58:59], v[48:49]
	v_pk_mul_f32 v[90:91], v[88:89], v[84:85]
	v_pk_fma_f32 v[92:93], v[18:19], v[12:13], v[0:1]
	v_pk_mul_f32 v[44:45], v[50:51], v[42:43]
	v_pk_mul_f32 v[102:103], v[92:93], v[90:91]
	v_pk_fma_f32 v[104:105], v[18:19], v[14:15], v[0:1]
	v_pk_mul_f32 v[40:41], v[44:45], v[38:39]
	v_pk_mul_f32 v[106:107], v[104:105], v[102:103]
	v_pk_fma_f32 v[108:109], v[18:19], v[16:17], v[0:1]
	v_pk_mul_f32 v[36:37], v[40:41], v[28:29]
	v_pk_mul_f32 v[110:111], v[108:109], v[106:107]
	ds_write2st64_b64 v95, v[36:37], v[110:111] offset1:8
	s_waitcnt lgkmcnt(0)
	s_barrier
	ds_read2st64_b64 v[8:11], v21 offset1:1
	ds_read2st64_b64 v[12:15], v21 offset0:2 offset1:3
	ds_read2st64_b64 v[0:3], v21 offset0:9 offset1:10
	v_lshlrev_b32_e32 v118, 16, v112
	v_and_b32_e32 v112, 0xffff0000, v112
	s_waitcnt lgkmcnt(2)
	v_cndmask_b32_e64 v4, v9, 1.0, s[0:1]
	v_cndmask_b32_e64 v5, v8, 1.0, s[0:1]
	v_mul_f32_e32 v6, v5, v10
	v_mul_f32_e32 v7, v4, v11
	v_cndmask_b32_e64 v16, v4, v7, s[2:3]
	v_cndmask_b32_e64 v17, v5, v6, s[2:3]
	s_waitcnt lgkmcnt(1)
	v_mul_f32_e32 v52, v17, v12
	v_mul_f32_e32 v53, v16, v13
	v_cndmask_b32_e64 v16, v16, v53, s[4:5]
	v_cndmask_b32_e64 v17, v17, v52, s[4:5]
	v_pk_mul_f32 v[8:9], v[8:9], v[10:11]
	ds_read2st64_b64 v[4:7], v21 offset0:11 offset1:12
	v_mul_f32_e32 v52, v17, v14
	v_mul_f32_e32 v53, v16, v15
	v_pk_mul_f32 v[8:9], v[8:9], v[12:13]
	v_cndmask_b32_e64 v16, v16, v53, s[8:9]
	v_cndmask_b32_e64 v17, v17, v52, s[8:9]
	v_pk_mul_f32 v[52:53], v[8:9], v[14:15]
	ds_read2st64_b64 v[8:11], v21 offset0:4 offset1:5
	s_waitcnt lgkmcnt(2)
	v_cndmask_b32_e64 v18, 1.0, v1, s[0:1]
	v_cndmask_b32_e64 v19, 1.0, v0, s[0:1]
	v_mul_f32_e32 v19, v19, v2
	v_mul_f32_e32 v18, v18, v3
	v_cndmask_b32_e64 v18, 1.0, v18, s[6:7]
	v_cndmask_b32_e64 v19, 1.0, v19, s[6:7]
	s_waitcnt lgkmcnt(1)
	v_mul_f32_e32 v12, v19, v4
	v_mul_f32_e32 v13, v18, v5
	v_cndmask_b32_e64 v18, 1.0, v13, s[10:11]
	v_cndmask_b32_e64 v19, 1.0, v12, s[10:11]
	ds_read2st64_b64 v[12:15], v21 offset0:6 offset1:7
	s_waitcnt lgkmcnt(1)
	v_mul_f32_e32 v66, v17, v8
	v_mul_f32_e32 v67, v16, v9
	v_cndmask_b32_e64 v67, v16, v67, s[12:13]
	v_cndmask_b32_e64 v66, v17, v66, s[12:13]
	v_mul_f32_e32 v16, v19, v6
	v_mul_f32_e32 v17, v18, v7
	v_cndmask_b32_e64 v68, 1.0, v17, s[14:15]
	v_cndmask_b32_e64 v69, 1.0, v16, s[14:15]
	ds_read2st64_b64 v[16:19], v21 offset0:13 offset1:14
	v_mul_f32_e32 v70, v66, v10
	v_mul_f32_e32 v71, v67, v11
	v_cndmask_b32_e64 v67, v67, v71, s[16:17]
	v_cndmask_b32_e64 v66, v66, v70, s[16:17]
	ds_read_b64 v[70:71], v21 offset:7680
	s_waitcnt lgkmcnt(1)
	v_mul_f32_e32 v69, v69, v16
	v_mul_f32_e32 v68, v68, v17
	v_cndmask_b32_e64 v68, 1.0, v68, s[18:19]
	v_cndmask_b32_e64 v69, 1.0, v69, s[18:19]
	v_mul_f32_e32 v74, v66, v12
	v_mul_f32_e32 v75, v67, v13
	v_cndmask_b32_e64 v67, v67, v75, s[20:21]
	v_cndmask_b32_e64 v66, v66, v74, s[20:21]
	v_mul_f32_e32 v69, v69, v18
	v_mul_f32_e32 v68, v68, v19
	v_cndmask_b32_e64 v68, 1.0, v68, s[22:23]
	v_cndmask_b32_e64 v69, 1.0, v69, s[22:23]
	v_mul_f32_e32 v74, v66, v14
	v_mul_f32_e32 v75, v67, v15
	v_cndmask_b32_e64 v114, v67, v75, s[24:25]
	v_cndmask_b32_e64 v115, v66, v74, s[24:25]
	s_waitcnt lgkmcnt(0)
	v_mul_f32_e32 v66, v69, v70
	v_mul_f32_e32 v67, v68, v71
	v_cndmask_b32_e64 v116, 1.0, v67, s[26:27]
	v_cndmask_b32_e64 v117, 1.0, v66, s[26:27]
	v_pk_mul_f32 v[66:67], v[6:7], v[16:17]
	v_rcp_f32_e32 v74, v52
	v_pk_mul_f32 v[66:67], v[66:67], v[18:19]
	v_rcp_f32_e32 v75, v53
	v_pk_mul_f32 v[68:69], v[66:67], v[70:71]
	v_mul_f32_e32 v115, v74, v115
	v_rcp_f32_e32 v66, v68
	v_rcp_f32_e32 v67, v69
	v_mul_f32_e32 v114, v75, v114
	v_mul_f32_e32 v119, v86, v115
	v_mul_f32_e32 v117, v66, v117
	v_mul_f32_e32 v116, v67, v116
	v_mul_f32_e32 v120, v87, v114
	v_mul_f32_e32 v121, v110, v117
	v_mul_f32_e32 v122, v111, v116
	v_rcp_f32_e32 v110, v119
	v_rcp_f32_e32 v111, v120
	v_mul_f32_e32 v123, v119, v118
	v_mul_f32_e32 v124, v120, v112
	v_cvt_pk_bf16_f32 v119, v123, v124
	global_store_dword v[34:35], v119, off nt
	v_pk_add_f32 v[34:35], v[86:87], 1.0 op_sel_hi:[1,0] neg_lo:[1,0] neg_hi:[1,0]
	v_and_b32_e32 v87, 0xffff0000, v113
	v_pk_mul_f32 v[34:35], v[34:35], v[110:111]
	v_pk_add_f32 v[28:29], v[28:29], 1.0 op_sel_hi:[1,0] neg_lo:[1,0] neg_hi:[1,0]
	v_cvt_pk_bf16_f32 v34, v34, v35
	global_store_dword v[32:33], v34, off nt
	v_mul_f32_e32 v32, v121, v118
	v_mul_f32_e32 v33, v122, v112
	v_cvt_pk_bf16_f32 v86, v32, v33
	v_rcp_f32_e32 v32, v121
	v_rcp_f32_e32 v33, v122
	v_lshl_add_u64 v[34:35], s[40:41], 0, v[26:27]
	global_store_dword v[34:35], v86, off nt
	v_pk_add_f32 v[34:35], v[108:109], 1.0 op_sel_hi:[1,0] neg_lo:[1,0] neg_hi:[1,0]
	v_lshlrev_b32_e32 v86, 16, v113
	v_pk_mul_f32 v[32:33], v[34:35], v[32:33]
	s_nop 0
	v_cvt_pk_bf16_f32 v32, v32, v33
	global_store_dword v[30:31], v32, off nt
	v_mul_f32_e32 v32, v82, v115
	v_mul_f32_e32 v33, v83, v114
	v_mul_f32_e32 v30, v32, v86
	v_mul_f32_e32 v31, v33, v87
	v_rcp_f32_e32 v32, v32
	v_rcp_f32_e32 v33, v33
	v_mul_f32_e32 v82, v106, v117
	v_cvt_pk_bf16_f32 v106, v30, v31
	v_or_b32_e32 v30, 0x800, v26
	v_mov_b32_e32 v31, v27
	v_lshl_add_u64 v[34:35], s[34:35], 0, v[30:31]
	global_store_dword v[34:35], v106, off nt
	v_pk_add_f32 v[34:35], v[78:79], 1.0 op_sel_hi:[1,0] neg_lo:[1,0] neg_hi:[1,0]
	v_mul_f32_e32 v83, v107, v116
	v_pk_mul_f32 v[32:33], v[34:35], v[32:33]
	v_and_b32_e32 v79, 0xffff0000, v101
	v_cvt_pk_bf16_f32 v34, v32, v33
	v_lshl_add_u64 v[32:33], s[36:37], 0, v[30:31]
	global_store_dword v[32:33], v34, off nt
	v_mul_f32_e32 v32, v82, v86
	v_mul_f32_e32 v33, v83, v87
	v_cvt_pk_bf16_f32 v78, v32, v33
	v_rcp_f32_e32 v32, v82
	v_rcp_f32_e32 v33, v83
	v_lshl_add_u64 v[34:35], s[40:41], 0, v[30:31]
	global_store_dword v[34:35], v78, off nt
	v_pk_add_f32 v[34:35], v[104:105], 1.0 op_sel_hi:[1,0] neg_lo:[1,0] neg_hi:[1,0]
	v_lshl_add_u64 v[30:31], s[38:39], 0, v[30:31]
	v_pk_mul_f32 v[32:33], v[34:35], v[32:33]
	v_lshlrev_b32_e32 v78, 16, v101
	v_cvt_pk_bf16_f32 v32, v32, v33
	global_store_dword v[30:31], v32, off nt
	v_mul_f32_e32 v32, v72, v115
	v_mul_f32_e32 v33, v73, v114
	v_mul_f32_e32 v30, v32, v78
	v_mul_f32_e32 v31, v33, v79
	v_rcp_f32_e32 v32, v32
	v_rcp_f32_e32 v33, v33
	v_cvt_pk_bf16_f32 v82, v30, v31
	v_or_b32_e32 v30, 0x1000, v26
	v_mov_b32_e32 v31, v27
	v_lshl_add_u64 v[34:35], s[34:35], 0, v[30:31]
	global_store_dword v[34:35], v82, off nt
	v_pk_add_f32 v[34:35], v[64:65], 1.0 op_sel_hi:[1,0] neg_lo:[1,0] neg_hi:[1,0]
	v_mul_f32_e32 v72, v102, v117
	v_pk_mul_f32 v[32:33], v[34:35], v[32:33]
	v_mul_f32_e32 v73, v103, v116
	v_cvt_pk_bf16_f32 v34, v32, v33
	v_lshl_add_u64 v[32:33], s[36:37], 0, v[30:31]
	global_store_dword v[32:33], v34, off nt
	v_mul_f32_e32 v32, v72, v78
	v_mul_f32_e32 v33, v73, v79
	v_cvt_pk_bf16_f32 v64, v32, v33
	v_rcp_f32_e32 v32, v72
	v_rcp_f32_e32 v33, v73
	v_lshl_add_u64 v[34:35], s[40:41], 0, v[30:31]
	global_store_dword v[34:35], v64, off nt
	v_pk_add_f32 v[34:35], v[92:93], 1.0 op_sel_hi:[1,0] neg_lo:[1,0] neg_hi:[1,0]
	v_lshl_add_u64 v[30:31], s[38:39], 0, v[30:31]
	v_pk_mul_f32 v[32:33], v[34:35], v[32:33]
	v_lshlrev_b32_e32 v64, 16, v99
	v_cvt_pk_bf16_f32 v32, v32, v33
	global_store_dword v[30:31], v32, off nt
	v_and_b32_e32 v65, 0xffff0000, v99
	v_mul_f32_e32 v32, v58, v115
	v_mul_f32_e32 v33, v59, v114
	v_mul_f32_e32 v30, v32, v64
	v_mul_f32_e32 v31, v33, v65
	v_rcp_f32_e32 v32, v32
	v_rcp_f32_e32 v33, v33
	v_cvt_pk_bf16_f32 v72, v30, v31
	v_or_b32_e32 v30, 0x1800, v26
	v_mov_b32_e32 v31, v27
	v_lshl_add_u64 v[34:35], s[34:35], 0, v[30:31]
	global_store_dword v[34:35], v72, off nt
	v_pk_add_f32 v[34:35], v[56:57], 1.0 op_sel_hi:[1,0] neg_lo:[1,0] neg_hi:[1,0]
	v_mul_f32_e32 v58, v90, v117
	v_pk_mul_f32 v[32:33], v[34:35], v[32:33]
	v_mul_f32_e32 v59, v91, v116
	v_cvt_pk_bf16_f32 v34, v32, v33
	v_lshl_add_u64 v[32:33], s[36:37], 0, v[30:31]
	global_store_dword v[32:33], v34, off nt
	v_mul_f32_e32 v32, v58, v64
	v_mul_f32_e32 v33, v59, v65
	v_cvt_pk_bf16_f32 v56, v32, v33
	v_rcp_f32_e32 v32, v58
	v_rcp_f32_e32 v33, v59
	v_lshl_add_u64 v[34:35], s[40:41], 0, v[30:31]
	global_store_dword v[34:35], v56, off nt
	v_pk_add_f32 v[34:35], v[88:89], 1.0 op_sel_hi:[1,0] neg_lo:[1,0] neg_hi:[1,0]
	v_lshl_add_u64 v[30:31], s[38:39], 0, v[30:31]
	v_pk_mul_f32 v[32:33], v[34:35], v[32:33]
	v_lshlrev_b32_e32 v56, 16, v100
	v_cvt_pk_bf16_f32 v32, v32, v33
	global_store_dword v[30:31], v32, off nt
	v_and_b32_e32 v57, 0xffff0000, v100
	v_mul_f32_e32 v32, v50, v115
	v_mul_f32_e32 v33, v51, v114
	v_mul_f32_e32 v30, v32, v56
	v_mul_f32_e32 v31, v33, v57
	v_rcp_f32_e32 v32, v32
	v_rcp_f32_e32 v33, v33
	v_cvt_pk_bf16_f32 v58, v30, v31
	v_or_b32_e32 v30, 0x2000, v26
	v_mov_b32_e32 v31, v27
	v_lshl_add_u64 v[34:35], s[34:35], 0, v[30:31]
	global_store_dword v[34:35], v58, off nt
	v_pk_add_f32 v[34:35], v[48:49], 1.0 op_sel_hi:[1,0] neg_lo:[1,0] neg_hi:[1,0]
	v_mul_f32_e32 v50, v84, v117
	v_pk_mul_f32 v[32:33], v[34:35], v[32:33]
	v_mul_f32_e32 v51, v85, v116
	v_cvt_pk_bf16_f32 v34, v32, v33
	v_lshl_add_u64 v[32:33], s[36:37], 0, v[30:31]
	global_store_dword v[32:33], v34, off nt
	v_mul_f32_e32 v32, v50, v56
	v_mul_f32_e32 v33, v51, v57
	v_cvt_pk_bf16_f32 v48, v32, v33
	v_rcp_f32_e32 v32, v50
	v_rcp_f32_e32 v33, v51
	v_lshl_add_u64 v[34:35], s[40:41], 0, v[30:31]
	global_store_dword v[34:35], v48, off nt
	v_pk_add_f32 v[34:35], v[80:81], 1.0 op_sel_hi:[1,0] neg_lo:[1,0] neg_hi:[1,0]
	v_lshl_add_u64 v[30:31], s[38:39], 0, v[30:31]
	v_pk_mul_f32 v[32:33], v[34:35], v[32:33]
	v_lshlrev_b32_e32 v48, 16, v98
	v_cvt_pk_bf16_f32 v32, v32, v33
	global_store_dword v[30:31], v32, off nt
	v_and_b32_e32 v49, 0xffff0000, v98
	v_mul_f32_e32 v32, v44, v115
	v_mul_f32_e32 v33, v45, v114
	v_mul_f32_e32 v30, v32, v48
	v_mul_f32_e32 v31, v33, v49
	v_rcp_f32_e32 v32, v32
	v_rcp_f32_e32 v33, v33
	v_cvt_pk_bf16_f32 v50, v30, v31
	v_or_b32_e32 v30, 0x2800, v26
	v_mov_b32_e32 v31, v27
	v_lshl_add_u64 v[34:35], s[34:35], 0, v[30:31]
	global_store_dword v[34:35], v50, off nt
	v_pk_add_f32 v[34:35], v[42:43], 1.0 op_sel_hi:[1,0] neg_lo:[1,0] neg_hi:[1,0]
	v_mul_f32_e32 v44, v76, v117
	v_pk_mul_f32 v[32:33], v[34:35], v[32:33]
	v_mul_f32_e32 v45, v77, v116
	v_cvt_pk_bf16_f32 v34, v32, v33
	v_lshl_add_u64 v[32:33], s[36:37], 0, v[30:31]
	global_store_dword v[32:33], v34, off nt
	v_mul_f32_e32 v32, v44, v48
	v_mul_f32_e32 v33, v45, v49
	v_cvt_pk_bf16_f32 v42, v32, v33
	v_rcp_f32_e32 v32, v44
	v_rcp_f32_e32 v33, v45
	v_lshl_add_u64 v[34:35], s[40:41], 0, v[30:31]
	global_store_dword v[34:35], v42, off nt
	v_pk_add_f32 v[34:35], v[62:63], 1.0 op_sel_hi:[1,0] neg_lo:[1,0] neg_hi:[1,0]
	v_lshl_add_u64 v[30:31], s[38:39], 0, v[30:31]
	v_pk_mul_f32 v[32:33], v[34:35], v[32:33]
	s_waitcnt vmcnt(24)
	v_lshlrev_b32_e32 v42, 16, v97
	v_cvt_pk_bf16_f32 v32, v32, v33
	global_store_dword v[30:31], v32, off nt
	v_and_b32_e32 v43, 0xffff0000, v97
	v_mul_f32_e32 v32, v40, v115
	v_mul_f32_e32 v33, v41, v114
	v_mul_f32_e32 v30, v32, v42
	v_mul_f32_e32 v31, v33, v43
	v_rcp_f32_e32 v32, v32
	v_rcp_f32_e32 v33, v33
	v_cvt_pk_bf16_f32 v44, v30, v31
	v_or_b32_e32 v30, 0x3000, v26
	v_mov_b32_e32 v31, v27
	v_lshl_add_u64 v[34:35], s[34:35], 0, v[30:31]
	global_store_dword v[34:35], v44, off nt
	v_pk_add_f32 v[34:35], v[38:39], 1.0 op_sel_hi:[1,0] neg_lo:[1,0] neg_hi:[1,0]
	v_mul_f32_e32 v40, v60, v117
	v_pk_mul_f32 v[32:33], v[34:35], v[32:33]
	v_mul_f32_e32 v41, v61, v116
	v_cvt_pk_bf16_f32 v34, v32, v33
	v_lshl_add_u64 v[32:33], s[36:37], 0, v[30:31]
	global_store_dword v[32:33], v34, off nt
	v_mul_f32_e32 v32, v40, v42
	v_mul_f32_e32 v33, v41, v43
	v_cvt_pk_bf16_f32 v38, v32, v33
	v_rcp_f32_e32 v32, v40
	v_rcp_f32_e32 v33, v41
	v_lshl_add_u64 v[34:35], s[40:41], 0, v[30:31]
	global_store_dword v[34:35], v38, off nt
	v_pk_add_f32 v[34:35], v[54:55], 1.0 op_sel_hi:[1,0] neg_lo:[1,0] neg_hi:[1,0]
	v_lshl_add_u64 v[30:31], s[38:39], 0, v[30:31]
	v_pk_mul_f32 v[32:33], v[34:35], v[32:33]
	s_waitcnt vmcnt(27)
	v_lshlrev_b32_e32 v34, 16, v22
	v_cvt_pk_bf16_f32 v32, v32, v33
	global_store_dword v[30:31], v32, off nt
	v_and_b32_e32 v22, 0xffff0000, v22
	v_mul_f32_e32 v30, v36, v115
	v_mul_f32_e32 v31, v37, v114
	v_mul_f32_e32 v32, v30, v34
	v_mul_f32_e32 v33, v31, v22
	v_rcp_f32_e32 v30, v30
	v_rcp_f32_e32 v31, v31
	v_or_b32_e32 v26, 0x3800, v26
	v_mul_f32_e32 v35, v46, v117
	v_mul_f32_e32 v36, v47, v116
	v_pk_mul_f32 v[28:29], v[28:29], v[30:31]
	v_mul_f32_e32 v22, v36, v22
	v_cvt_pk_bf16_f32 v30, v28, v29
	v_lshl_add_u64 v[28:29], s[36:37], 0, v[26:27]
	global_store_dword v[28:29], v30, off nt
	v_mul_f32_e32 v28, v35, v34
	v_cvt_pk_bf16_f32 v22, v28, v22
	v_rcp_f32_e32 v28, v35
	v_rcp_f32_e32 v29, v36
	v_lshl_add_u64 v[30:31], s[40:41], 0, v[26:27]
	global_store_dword v[30:31], v22, off nt
	v_pk_add_f32 v[30:31], v[46:47], 1.0 op_sel_hi:[1,0] neg_lo:[1,0] neg_hi:[1,0]
	v_cvt_pk_bf16_f32 v37, v32, v33
	v_pk_mul_f32 v[28:29], v[30:31], v[28:29]
	v_lshl_add_u64 v[32:33], s[34:35], 0, v[26:27]
	v_cvt_pk_bf16_f32 v22, v28, v29
	v_lshl_add_u64 v[26:27], s[38:39], 0, v[26:27]
	global_store_dword v[32:33], v37, off nt
	global_store_dword v[26:27], v22, off nt
	s_and_saveexec_b64 s[44:45], s[0:1]
	s_cbranch_execz .LBB0_551
	ds_read_b64 v[26:27], v21 offset:4096
	s_lshl_b32 s42, s42, 3
	v_pk_mul_f32 v[8:9], v[52:53], v[8:9]
	s_or_b32 s42, s42, s50
	v_pk_mul_f32 v[8:9], v[8:9], v[10:11]
	s_waitcnt lgkmcnt(0)
	v_pk_mul_f32 v[0:1], v[26:27], v[0:1]
	s_lshl_b32 s43, s42, 7
	v_pk_mul_f32 v[0:1], v[0:1], v[2:3]
	s_add_i32 s42, s42, 32
	v_pk_mul_f32 v[8:9], v[8:9], v[12:13]
	v_pk_mul_f32 v[0:1], v[0:1], v[4:5]
	s_or_b32 s50, s43, s49
	s_ashr_i32 s43, s42, 31
	v_pk_mul_f32 v[8:9], v[8:9], v[14:15]
	v_pk_mul_f32 v[0:1], v[0:1], v[6:7]
	s_lshl_b64 s[42:43], s[42:43], 7
	s_xor_b32 s49, s49, 0x7f
	v_pk_mul_f32 v[0:1], v[0:1], v[16:17]
	s_or_b32 s42, s42, s49
	v_mad_i64_i32 v[2:3], s[50:51], s50, v96, v[24:25]
	v_pk_mul_f32 v[4:5], v[74:75], v[8:9]
	v_pk_mul_f32 v[0:1], v[0:1], v[18:19]
	global_store_dwordx2 v[2:3], v[52:53], off
	global_store_dwordx2 v[2:3], v[8:9], off offset:512
	global_store_dwordx2 v[2:3], v[4:5], off offset:1024
	s_mul_i32 s49, s43, 0x600
	v_mad_u64_u32 v[2:3], s[42:43], s42, v96, v[24:25]
	v_pk_mul_f32 v[0:1], v[0:1], v[70:71]
	v_add_u32_e32 v3, s49, v3
	global_store_dwordx2 v[2:3], v[68:69], off
	global_store_dwordx2 v[2:3], v[0:1], off offset:512
	v_pk_mul_f32 v[0:1], v[0:1], v[66:67]
	global_store_dwordx2 v[2:3], v[0:1], off offset:1024
	s_branch .LBB0_551
